# context hyena task input conv: all 48 loads (12 per-channel scalars once + 36 tokens) issued together instead of ~3 dependent load/wait round trips per (batch, stream) value
# baseline (speedup 1.0000x reference)
.LBB0_701:
	s_or_b64 exec, exec, s[2:3]
	v_add_u32_e32 v0, 0x100, v8
	v_ashrrev_i32_e32 v1, 31, v0
	v_ashrrev_i32_e32 v9, 31, v8
	v_mov_b32_e32 v14, 0
	v_lshl_add_u64 v[10:11], v[0:1], 2, s[36:37]
	v_lshl_add_u64 v[12:13], v[8:9], 2, s[36:37]
	s_mov_b32 s0, 0
	v_readlane_b32 s1, v254, 40
	v_mov_b32_e32 v15, v14
	s_waitcnt lgkmcnt(0)
	s_barrier
	v_mov_b32_e32 v17, s1
	v_lshlrev_b32_e32 v30, 2, v8
	s_mov_b32 s0, s36
	s_mov_b32 s1, s37
	global_load_dword v194, v30, s[0:1]
	s_add_u32 s0, s0, 0x400
	s_addc_u32 s1, s1, 0
	global_load_dword v195, v30, s[0:1]
	s_add_u32 s0, s0, 0x400
	s_addc_u32 s1, s1, 0
	global_load_dword v196, v30, s[0:1]
	s_add_u32 s0, s0, 0x400
	s_addc_u32 s1, s1, 0
	global_load_dword v197, v30, s[0:1]
	s_add_u32 s0, s0, 0x400
	s_addc_u32 s1, s1, 0
	global_load_dword v198, v30, s[0:1]
	s_add_u32 s0, s0, 0x400
	s_addc_u32 s1, s1, 0
	global_load_dword v199, v30, s[0:1]
	s_add_u32 s0, s0, 0x400
	s_addc_u32 s1, s1, 0
	global_load_dword v200, v30, s[0:1]
	s_add_u32 s0, s0, 0x400
	s_addc_u32 s1, s1, 0
	global_load_dword v201, v30, s[0:1]
	s_add_u32 s0, s0, 0x400
	s_addc_u32 s1, s1, 0
	global_load_dword v202, v30, s[0:1]
	s_add_u32 s0, s0, 0x400
	s_addc_u32 s1, s1, 0
	global_load_dword v203, v30, s[0:1]
	s_add_u32 s0, s0, 0x400
	s_addc_u32 s1, s1, 0
	global_load_dword v204, v30, s[0:1]
	s_add_u32 s0, s0, 0x400
	s_addc_u32 s1, s1, 0
	global_load_dword v205, v30, s[0:1]
	s_add_u32 s0, s0, 0x400
	s_addc_u32 s1, s1, 0
	global_load_dword v206, v30, s[0:1]
	s_add_u32 s0, s0, 0x400
	s_addc_u32 s1, s1, 0
	global_load_dword v207, v30, s[0:1]
	s_add_u32 s0, s0, 0x400
	s_addc_u32 s1, s1, 0
	global_load_dword v208, v30, s[0:1]
	s_add_u32 s0, s0, 0x400
	s_addc_u32 s1, s1, 0
	global_load_dword v209, v30, s[0:1]
	s_add_u32 s0, s0, 0x400
	s_addc_u32 s1, s1, 0
	global_load_dword v210, v30, s[0:1]
	s_add_u32 s0, s0, 0x400
	s_addc_u32 s1, s1, 0
	global_load_dword v211, v30, s[0:1]
	s_add_u32 s0, s0, 0x400
	s_addc_u32 s1, s1, 0
	global_load_dword v212, v30, s[0:1]
	s_add_u32 s0, s0, 0x400
	s_addc_u32 s1, s1, 0
	global_load_dword v213, v30, s[0:1]
	s_add_u32 s0, s0, 0x400
	s_addc_u32 s1, s1, 0
	global_load_dword v214, v30, s[0:1]
	s_add_u32 s0, s0, 0x400
	s_addc_u32 s1, s1, 0
	global_load_dword v215, v30, s[0:1]
	s_add_u32 s0, s0, 0x400
	s_addc_u32 s1, s1, 0
	global_load_dword v216, v30, s[0:1]
	s_add_u32 s0, s0, 0x400
	s_addc_u32 s1, s1, 0
	global_load_dword v217, v30, s[0:1]
	s_add_u32 s0, s0, 0x400
	s_addc_u32 s1, s1, 0
	global_load_dword v218, v30, s[0:1]
	s_add_u32 s0, s0, 0x400
	s_addc_u32 s1, s1, 0
	global_load_dword v219, v30, s[0:1]
	s_add_u32 s0, s0, 0x400
	s_addc_u32 s1, s1, 0
	global_load_dword v220, v30, s[0:1]
	s_add_u32 s0, s0, 0x400
	s_addc_u32 s1, s1, 0
	global_load_dword v221, v30, s[0:1]
	s_add_u32 s0, s0, 0x400
	s_addc_u32 s1, s1, 0
	global_load_dword v222, v30, s[0:1]
	s_add_u32 s0, s0, 0x400
	s_addc_u32 s1, s1, 0
	global_load_dword v223, v30, s[0:1]
	s_add_u32 s0, s0, 0x400
	s_addc_u32 s1, s1, 0
	global_load_dword v224, v30, s[0:1]
	s_add_u32 s0, s0, 0x400
	s_addc_u32 s1, s1, 0
	global_load_dword v225, v30, s[0:1]
	s_add_u32 s0, s0, 0x400
	s_addc_u32 s1, s1, 0
	global_load_dword v226, v30, s[0:1]
	s_add_u32 s0, s0, 0x400
	s_addc_u32 s1, s1, 0
	global_load_dword v227, v30, s[0:1]
	s_add_u32 s0, s0, 0x400
	s_addc_u32 s1, s1, 0
	global_load_dword v228, v30, s[0:1]
	s_add_u32 s0, s0, 0x400
	s_addc_u32 s1, s1, 0
	global_load_dword v229, v30, s[0:1]
	s_add_u32 s0, s0, 0x400
	s_addc_u32 s1, s1, 0
	global_load_dword v230, v30, s[0:1]
	s_add_u32 s0, s0, 0x400
	s_addc_u32 s1, s1, 0
	global_load_dword v231, v30, s[0:1]
	s_add_u32 s0, s0, 0x400
	s_addc_u32 s1, s1, 0
	global_load_dword v232, v30, s[0:1]
	s_add_u32 s0, s0, 0x400
	s_addc_u32 s1, s1, 0
	global_load_dword v233, v30, s[0:1]
	s_add_u32 s0, s0, 0x400
	s_addc_u32 s1, s1, 0
	global_load_dword v234, v30, s[0:1]
	s_add_u32 s0, s0, 0x400
	s_addc_u32 s1, s1, 0
	global_load_dword v235, v30, s[0:1]
	s_add_u32 s0, s0, 0x400
	s_addc_u32 s1, s1, 0
	global_load_dword v236, v30, s[0:1]
	s_add_u32 s0, s0, 0x400
	s_addc_u32 s1, s1, 0
	global_load_dword v237, v30, s[0:1]
	s_add_u32 s0, s0, 0x400
	s_addc_u32 s1, s1, 0
	global_load_dword v238, v30, s[0:1]
	s_add_u32 s0, s0, 0x400
	s_addc_u32 s1, s1, 0
	global_load_dword v239, v30, s[0:1]
	s_add_u32 s0, s0, 0x400
	s_addc_u32 s1, s1, 0
	global_load_dword v240, v30, s[0:1]
	s_add_u32 s0, s0, 0x400
	s_addc_u32 s1, s1, 0
	global_load_dword v241, v30, s[0:1]
	s_add_u32 s0, s0, 0x400
	s_addc_u32 s1, s1, 0
	global_load_dword v242, v30, s[0:1]
	s_add_u32 s0, s0, 0x400
	s_addc_u32 s1, s1, 0
	global_load_dword v243, v30, s[0:1]
	s_add_u32 s0, s0, 0x400
	s_addc_u32 s1, s1, 0
	global_load_dword v244, v30, s[0:1]
	s_add_u32 s0, s0, 0x400
	s_addc_u32 s1, s1, 0
	global_load_dword v245, v30, s[0:1]
	s_add_u32 s0, s0, 0x400
	s_addc_u32 s1, s1, 0
	global_load_dword v246, v30, s[0:1]
	s_add_u32 s0, s0, 0x400
	s_addc_u32 s1, s1, 0
	global_load_dword v247, v30, s[0:1]
	s_add_u32 s0, s0, 0x400
	s_addc_u32 s1, s1, 0
	global_load_dword v248, v30, s[0:1]
	s_add_u32 s0, s0, 0x400
	s_addc_u32 s1, s1, 0
	global_load_dword v249, v30, s[0:1]
	s_add_u32 s0, s0, 0x400
	s_addc_u32 s1, s1, 0
	global_load_dword v250, v30, s[0:1]
	s_add_u32 s0, s0, 0x400
	s_addc_u32 s1, s1, 0
	global_load_dword v251, v30, s[0:1]
	s_add_u32 s0, s0, 0x400
	s_addc_u32 s1, s1, 0
	global_load_dword v252, v30, s[0:1]
	s_add_u32 s0, s0, 0x400
	s_addc_u32 s1, s1, 0
	global_load_dword v253, v30, s[0:1]
	s_add_u32 s0, s0, 0x400
	s_addc_u32 s1, s1, 0
	ds_read_b128 v[18:21], v17
	ds_read_b128 v[22:25], v17 offset:256
	ds_read_b128 v[0:3], v17 offset:16
	ds_read_b128 v[4:7], v17 offset:272
	s_waitcnt vmcnt(28) lgkmcnt(2)
	v_fmac_f32_e32 v14, v194, v18
	v_fmac_f32_e32 v15, v194, v22
	v_fmac_f32_e32 v14, v195, v19
	v_fmac_f32_e32 v15, v195, v23
	v_fmac_f32_e32 v14, v196, v20
	v_fmac_f32_e32 v15, v196, v24
	v_fmac_f32_e32 v14, v197, v21
	v_fmac_f32_e32 v15, v197, v25
	ds_read_b128 v[18:21], v17 offset:32
	ds_read_b128 v[22:25], v17 offset:288
	s_waitcnt lgkmcnt(2)
	v_fmac_f32_e32 v14, v198, v0
	v_fmac_f32_e32 v15, v198, v4
	v_fmac_f32_e32 v14, v199, v1
	v_fmac_f32_e32 v15, v199, v5
	v_fmac_f32_e32 v14, v200, v2
	v_fmac_f32_e32 v15, v200, v6
	v_fmac_f32_e32 v14, v201, v3
	v_fmac_f32_e32 v15, v201, v7
	ds_read_b128 v[0:3], v17 offset:48
	ds_read_b128 v[4:7], v17 offset:304
	s_waitcnt lgkmcnt(2)
	v_fmac_f32_e32 v14, v202, v18
	v_fmac_f32_e32 v15, v202, v22
	v_fmac_f32_e32 v14, v203, v19
	v_fmac_f32_e32 v15, v203, v23
	v_fmac_f32_e32 v14, v204, v20
	v_fmac_f32_e32 v15, v204, v24
	v_fmac_f32_e32 v14, v205, v21
	v_fmac_f32_e32 v15, v205, v25
	ds_read_b128 v[18:21], v17 offset:64
	ds_read_b128 v[22:25], v17 offset:320
	s_waitcnt lgkmcnt(2)
	v_fmac_f32_e32 v14, v206, v0
	v_fmac_f32_e32 v15, v206, v4
	v_fmac_f32_e32 v14, v207, v1
	v_fmac_f32_e32 v15, v207, v5
	v_fmac_f32_e32 v14, v208, v2
	v_fmac_f32_e32 v15, v208, v6
	v_fmac_f32_e32 v14, v209, v3
	v_fmac_f32_e32 v15, v209, v7
	ds_read_b128 v[0:3], v17 offset:80
	ds_read_b128 v[4:7], v17 offset:336
	s_waitcnt lgkmcnt(2)
	v_fmac_f32_e32 v14, v210, v18
	v_fmac_f32_e32 v15, v210, v22
	v_fmac_f32_e32 v14, v211, v19
	v_fmac_f32_e32 v15, v211, v23
	v_fmac_f32_e32 v14, v212, v20
	v_fmac_f32_e32 v15, v212, v24
	v_fmac_f32_e32 v14, v213, v21
	v_fmac_f32_e32 v15, v213, v25
	ds_read_b128 v[18:21], v17 offset:96
	ds_read_b128 v[22:25], v17 offset:352
	s_waitcnt lgkmcnt(2)
	v_fmac_f32_e32 v14, v214, v0
	v_fmac_f32_e32 v15, v214, v4
	v_fmac_f32_e32 v14, v215, v1
	v_fmac_f32_e32 v15, v215, v5
	v_fmac_f32_e32 v14, v216, v2
	v_fmac_f32_e32 v15, v216, v6
	v_fmac_f32_e32 v14, v217, v3
	v_fmac_f32_e32 v15, v217, v7
	ds_read_b128 v[0:3], v17 offset:112
	ds_read_b128 v[4:7], v17 offset:368
	s_waitcnt lgkmcnt(2)
	v_fmac_f32_e32 v14, v218, v18
	v_fmac_f32_e32 v15, v218, v22
	v_fmac_f32_e32 v14, v219, v19
	v_fmac_f32_e32 v15, v219, v23
	v_fmac_f32_e32 v14, v220, v20
	v_fmac_f32_e32 v15, v220, v24
	v_fmac_f32_e32 v14, v221, v21
	v_fmac_f32_e32 v15, v221, v25
	ds_read_b128 v[18:21], v17 offset:128
	ds_read_b128 v[22:25], v17 offset:384
	s_waitcnt lgkmcnt(2)
	v_fmac_f32_e32 v14, v222, v0
	v_fmac_f32_e32 v15, v222, v4
	v_fmac_f32_e32 v14, v223, v1
	v_fmac_f32_e32 v15, v223, v5
	v_fmac_f32_e32 v14, v224, v2
	v_fmac_f32_e32 v15, v224, v6
	v_fmac_f32_e32 v14, v225, v3
	v_fmac_f32_e32 v15, v225, v7
	ds_read_b128 v[0:3], v17 offset:144
	ds_read_b128 v[4:7], v17 offset:400
	global_load_dword v26, v30, s[0:1]
	s_add_u32 s0, s0, 0x400
	s_addc_u32 s1, s1, 0
	global_load_dword v27, v30, s[0:1]
	s_add_u32 s0, s0, 0x400
	s_addc_u32 s1, s1, 0
	global_load_dword v28, v30, s[0:1]
	s_add_u32 s0, s0, 0x400
	s_addc_u32 s1, s1, 0
	global_load_dword v29, v30, s[0:1]
	s_add_u32 s0, s0, 0x400
	s_addc_u32 s1, s1, 0
	s_waitcnt vmcnt(0) lgkmcnt(2)
	v_fmac_f32_e32 v14, v226, v18
	v_fmac_f32_e32 v15, v226, v22
	v_fmac_f32_e32 v14, v227, v19
	v_fmac_f32_e32 v15, v227, v23
	v_fmac_f32_e32 v14, v228, v20
	v_fmac_f32_e32 v15, v228, v24
	v_fmac_f32_e32 v14, v229, v21
	v_fmac_f32_e32 v15, v229, v25
	ds_read_b128 v[18:21], v17 offset:160
	ds_read_b128 v[22:25], v17 offset:416
	s_waitcnt lgkmcnt(2)
	v_fmac_f32_e32 v14, v230, v0
	v_fmac_f32_e32 v15, v230, v4
	v_fmac_f32_e32 v14, v231, v1
	v_fmac_f32_e32 v15, v231, v5
	v_fmac_f32_e32 v14, v232, v2
	v_fmac_f32_e32 v15, v232, v6
	v_fmac_f32_e32 v14, v233, v3
	v_fmac_f32_e32 v15, v233, v7
	ds_read_b128 v[0:3], v17 offset:176
	ds_read_b128 v[4:7], v17 offset:432
	s_waitcnt lgkmcnt(2)
	v_fmac_f32_e32 v14, v234, v18
	v_fmac_f32_e32 v15, v234, v22
	v_fmac_f32_e32 v14, v235, v19
	v_fmac_f32_e32 v15, v235, v23
	v_fmac_f32_e32 v14, v236, v20
	v_fmac_f32_e32 v15, v236, v24
	v_fmac_f32_e32 v14, v237, v21
	v_fmac_f32_e32 v15, v237, v25
	ds_read_b128 v[18:21], v17 offset:192
	ds_read_b128 v[22:25], v17 offset:448
	s_waitcnt lgkmcnt(2)
	v_fmac_f32_e32 v14, v238, v0
	v_fmac_f32_e32 v15, v238, v4
	v_fmac_f32_e32 v14, v239, v1
	v_fmac_f32_e32 v15, v239, v5
	v_fmac_f32_e32 v14, v240, v2
	v_fmac_f32_e32 v15, v240, v6
	v_fmac_f32_e32 v14, v241, v3
	v_fmac_f32_e32 v15, v241, v7
	ds_read_b128 v[0:3], v17 offset:208
	ds_read_b128 v[4:7], v17 offset:464
	s_waitcnt lgkmcnt(2)
	v_fmac_f32_e32 v14, v242, v18
	v_fmac_f32_e32 v15, v242, v22
	v_fmac_f32_e32 v14, v243, v19
	v_fmac_f32_e32 v15, v243, v23
	v_fmac_f32_e32 v14, v244, v20
	v_fmac_f32_e32 v15, v244, v24
	v_fmac_f32_e32 v14, v245, v21
	v_fmac_f32_e32 v15, v245, v25
	ds_read_b128 v[18:21], v17 offset:224
	ds_read_b128 v[22:25], v17 offset:480
	s_waitcnt lgkmcnt(2)
	v_fmac_f32_e32 v14, v246, v0
	v_fmac_f32_e32 v15, v246, v4
	v_fmac_f32_e32 v14, v247, v1
	v_fmac_f32_e32 v15, v247, v5
	v_fmac_f32_e32 v14, v248, v2
	v_fmac_f32_e32 v15, v248, v6
	v_fmac_f32_e32 v14, v249, v3
	v_fmac_f32_e32 v15, v249, v7
	ds_read_b128 v[0:3], v17 offset:240
	ds_read_b128 v[4:7], v17 offset:496
	s_waitcnt lgkmcnt(2)
	v_fmac_f32_e32 v14, v250, v18
	v_fmac_f32_e32 v15, v250, v22
	v_fmac_f32_e32 v14, v251, v19
	v_fmac_f32_e32 v15, v251, v23
	v_fmac_f32_e32 v14, v252, v20
	v_fmac_f32_e32 v15, v252, v24
	v_fmac_f32_e32 v14, v253, v21
	v_fmac_f32_e32 v15, v253, v25
	s_waitcnt lgkmcnt(0)
	v_fmac_f32_e32 v14, v26, v0
	v_fmac_f32_e32 v15, v26, v4
	v_fmac_f32_e32 v14, v27, v1
	v_fmac_f32_e32 v15, v27, v5
	v_fmac_f32_e32 v14, v28, v2
	v_fmac_f32_e32 v15, v28, v6
	v_fmac_f32_e32 v14, v29, v3
	v_fmac_f32_e32 v15, v29, v7
	v_cvt_f32_i32_e32 v1, v8
	s_mov_b32 s2, 0xc37f0000
	v_cvt_f32_u32_e32 v0, s16
	s_lshl_b64 s[14:15], s[16:17], 9
	v_div_scale_f32 v2, s[0:1], s2, s2, v1
	v_rcp_f32_e32 v3, v2
	v_fmamk_f32 v0, v0, 0x3c44ade8, v186
	s_mov_b32 s0, 0x3fb8aa3b
	s_add_u32 s10, s26, s14
	v_fma_f32 v4, -v2, v3, 1.0
	v_fmac_f32_e32 v3, v4, v3
	v_div_scale_f32 v4, vcc, v1, s2, v1
	v_mul_f32_e32 v5, v4, v3
	v_fma_f32 v6, -v2, v5, v4
	v_fmac_f32_e32 v5, v6, v3
	v_fma_f32 v2, -v2, v5, v4
	v_div_fmas_f32 v2, v2, v3, v5
	v_div_fixup_f32 v1, v2, s2, v1
	v_mul_f32_e64 v0, |v0|, v1
	v_mul_f32_e32 v1, 0x3fb8aa3b, v0
	v_fma_f32 v2, v0, s0, -v1
	v_rndne_f32_e32 v3, v1
	v_fmac_f32_e32 v2, 0x32a5705f, v0
	v_sub_f32_e32 v1, v1, v3
	v_add_f32_e32 v1, v1, v2
	v_exp_f32_e32 v1, v1
	v_cvt_i32_f32_e32 v2, v3
	s_mov_b32 s0, 0xc2ce8ed0
	v_cmp_ngt_f32_e32 vcc, s0, v0
	s_mov_b32 s0, 0x42b17218
	v_ldexp_f32 v1, v1, v2
	v_cndmask_b32_e32 v1, 0, v1, vcc
	v_cmp_nlt_f32_e32 vcc, s0, v0
	s_addc_u32 s11, s27, s15
	s_lshl_b64 s[2:3], s[16:17], 2
	v_cndmask_b32_e32 v0, v190, v1, vcc
	s_add_u32 s0, s54, s2
	v_mul_f32_e32 v1, v0, v14
	v_mul_f32_e32 v0, v0, v15
	s_addc_u32 s1, s55, s3
	ds_write2st64_b32 v16, v1, v0 offset1:4
	s_lshl_b64 s[14:15], s[16:17], 9
	s_add_u32 s10, s26, s14
	s_addc_u32 s11, s27, s15
	v_lshl_add_u64 v[22:23], v[8:9], 1, s[10:11]
	v_mov_b32_e32 v242, v22
	v_mov_b32_e32 v243, v23
	s_mov_b64 s[8:9], 0x80000
	v_lshl_add_u64 v[244:245], v[22:23], 0, s[8:9]
	s_mov_b64 s[8:9], 0x100000
	v_lshl_add_u64 v[246:247], v[22:23], 0, s[8:9]
	s_mov_b64 s[8:9], 0x180000
	v_lshl_add_u64 v[248:249], v[22:23], 0, s[8:9]
	s_mov_b64 s[8:9], 0x200000
	v_lshl_add_u64 v[250:251], v[22:23], 0, s[8:9]
	s_mov_b64 s[8:9], 0x280000
	v_lshl_add_u64 v[252:253], v[22:23], 0, s[8:9]
	s_mov_b64 s[8:9], 0x300000
	v_lshl_add_u64 v[0:1], v[22:23], 0, s[8:9]
	s_mov_b64 s[8:9], 0x380000
	v_lshl_add_u64 v[2:3], v[22:23], 0, s[8:9]
	s_mov_b64 s[8:9], 0x400000
	v_lshl_add_u64 v[4:5], v[22:23], 0, s[8:9]
	s_mov_b64 s[8:9], 0x480000
	v_lshl_add_u64 v[6:7], v[22:23], 0, s[8:9]
	s_mov_b64 s[8:9], 0x500000
	v_lshl_add_u64 v[18:19], v[22:23], 0, s[8:9]
	s_mov_b64 s[8:9], 0x580000
	v_lshl_add_u64 v[20:21], v[22:23], 0, s[8:9]
	s_add_u32 s0, s54, s2
	s_addc_u32 s1, s55, s3
	s_add_u32 s12, s52, s2
	s_addc_u32 s13, s53, s3
	global_load_dword v230, v165, s[0:1]
	global_load_dword v231, v165, s[12:13]
	global_load_dword v232, v184, s[12:13]
	global_load_dword v233, v187, s[12:13]
	s_add_u32 s0, s0, 0x1000
	s_addc_u32 s1, s1, 0
	s_add_u32 s12, s12, 0x1000
	s_addc_u32 s13, s13, 0
	global_load_dword v234, v165, s[0:1]
	global_load_dword v235, v165, s[12:13]
	global_load_dword v236, v184, s[12:13]
	global_load_dword v237, v187, s[12:13]
	s_add_u32 s0, s0, 0x1000
	s_addc_u32 s1, s1, 0
	s_add_u32 s12, s12, 0x1000
	s_addc_u32 s13, s13, 0
	global_load_dword v238, v165, s[0:1]
	global_load_dword v239, v165, s[12:13]
	global_load_dword v240, v184, s[12:13]
	global_load_dword v241, v187, s[12:13]
	global_load_ushort v194, v[242:243], off
	global_load_ushort v195, v[244:245], off
	global_load_ushort v196, v[246:247], off
	global_load_ushort v197, v[248:249], off
	global_load_ushort v198, v[250:251], off
	global_load_ushort v199, v[252:253], off
	global_load_ushort v200, v[0:1], off
	global_load_ushort v201, v[2:3], off
	global_load_ushort v202, v[4:5], off
	global_load_ushort v203, v[6:7], off
	global_load_ushort v204, v[18:19], off
	global_load_ushort v205, v[20:21], off
	v_cmp_lt_i32_e32 vcc, 0, v8
	s_movk_i32 s0, 0xff
	v_cmp_gt_i32_e64 s[40:41], s0, v8
	s_mov_b64 s[42:43], exec
	s_and_b64 exec, s[42:43], vcc
	global_load_ushort v206, v[242:243], off offset:-2
	global_load_ushort v207, v[244:245], off offset:-2
	global_load_ushort v208, v[246:247], off offset:-2
	global_load_ushort v209, v[248:249], off offset:-2
	global_load_ushort v210, v[250:251], off offset:-2
	global_load_ushort v211, v[252:253], off offset:-2
	global_load_ushort v212, v[0:1], off offset:-2
	global_load_ushort v213, v[2:3], off offset:-2
	global_load_ushort v214, v[4:5], off offset:-2
	global_load_ushort v215, v[6:7], off offset:-2
	global_load_ushort v216, v[18:19], off offset:-2
	global_load_ushort v217, v[20:21], off offset:-2
	s_and_b64 exec, s[42:43], s[40:41]
	global_load_ushort v218, v[242:243], off offset:2
	global_load_ushort v219, v[244:245], off offset:2
	global_load_ushort v220, v[246:247], off offset:2
	global_load_ushort v221, v[248:249], off offset:2
	global_load_ushort v222, v[250:251], off offset:2
	global_load_ushort v223, v[252:253], off offset:2
	global_load_ushort v224, v[0:1], off offset:2
	global_load_ushort v225, v[2:3], off offset:2
	global_load_ushort v226, v[4:5], off offset:2
	global_load_ushort v227, v[6:7], off offset:2
	global_load_ushort v228, v[18:19], off offset:2
	global_load_ushort v229, v[20:21], off offset:2
	s_mov_b64 exec, s[42:43]
	s_waitcnt vmcnt(0)
	v_lshlrev_b32_e32 v194, 16, v194
	v_fma_f32 v194, v232, v194, v230
	v_lshlrev_b32_e32 v195, 16, v195
	v_fma_f32 v195, v236, v195, v234
	v_lshlrev_b32_e32 v196, 16, v196
	v_fma_f32 v196, v240, v196, v238
	v_lshlrev_b32_e32 v197, 16, v197
	v_fma_f32 v197, v232, v197, v230
	v_lshlrev_b32_e32 v198, 16, v198
	v_fma_f32 v198, v236, v198, v234
	v_lshlrev_b32_e32 v199, 16, v199
	v_fma_f32 v199, v240, v199, v238
	v_lshlrev_b32_e32 v200, 16, v200
	v_fma_f32 v200, v232, v200, v230
	v_lshlrev_b32_e32 v201, 16, v201
	v_fma_f32 v201, v236, v201, v234
	v_lshlrev_b32_e32 v202, 16, v202
	v_fma_f32 v202, v240, v202, v238
	v_lshlrev_b32_e32 v203, 16, v203
	v_fma_f32 v203, v232, v203, v230
	v_lshlrev_b32_e32 v204, 16, v204
	v_fma_f32 v204, v236, v204, v234
	v_lshlrev_b32_e32 v205, 16, v205
	v_fma_f32 v205, v240, v205, v238
	s_and_b64 exec, s[42:43], vcc
	v_lshlrev_b32_e32 v206, 16, v206
	v_fmac_f32_e32 v194, v231, v206
	v_lshlrev_b32_e32 v207, 16, v207
	v_fmac_f32_e32 v195, v235, v207
	v_lshlrev_b32_e32 v208, 16, v208
	v_fmac_f32_e32 v196, v239, v208
	v_lshlrev_b32_e32 v209, 16, v209
	v_fmac_f32_e32 v197, v231, v209
	v_lshlrev_b32_e32 v210, 16, v210
	v_fmac_f32_e32 v198, v235, v210
	v_lshlrev_b32_e32 v211, 16, v211
	v_fmac_f32_e32 v199, v239, v211
	v_lshlrev_b32_e32 v212, 16, v212
	v_fmac_f32_e32 v200, v231, v212
	v_lshlrev_b32_e32 v213, 16, v213
	v_fmac_f32_e32 v201, v235, v213
	v_lshlrev_b32_e32 v214, 16, v214
	v_fmac_f32_e32 v202, v239, v214
	v_lshlrev_b32_e32 v215, 16, v215
	v_fmac_f32_e32 v203, v231, v215
	v_lshlrev_b32_e32 v216, 16, v216
	v_fmac_f32_e32 v204, v235, v216
	v_lshlrev_b32_e32 v217, 16, v217
	v_fmac_f32_e32 v205, v239, v217
	s_and_b64 exec, s[42:43], s[40:41]
	v_lshlrev_b32_e32 v218, 16, v218
	v_fmac_f32_e32 v194, v233, v218
	v_lshlrev_b32_e32 v219, 16, v219
	v_fmac_f32_e32 v195, v237, v219
	v_lshlrev_b32_e32 v220, 16, v220
	v_fmac_f32_e32 v196, v241, v220
	v_lshlrev_b32_e32 v221, 16, v221
	v_fmac_f32_e32 v197, v233, v221
	v_lshlrev_b32_e32 v222, 16, v222
	v_fmac_f32_e32 v198, v237, v222
	v_lshlrev_b32_e32 v223, 16, v223
	v_fmac_f32_e32 v199, v241, v223
	v_lshlrev_b32_e32 v224, 16, v224
	v_fmac_f32_e32 v200, v233, v224
	v_lshlrev_b32_e32 v225, 16, v225
	v_fmac_f32_e32 v201, v237, v225
	v_lshlrev_b32_e32 v226, 16, v226
	v_fmac_f32_e32 v202, v241, v226
	v_lshlrev_b32_e32 v227, 16, v227
	v_fmac_f32_e32 v203, v233, v227
	v_lshlrev_b32_e32 v228, 16, v228
	v_fmac_f32_e32 v204, v237, v228
	v_lshlrev_b32_e32 v229, 16, v229
	v_fmac_f32_e32 v205, v241, v229
	s_mov_b64 exec, s[42:43]
	v_mov_b32_e32 v11, v194
	v_mul_f32_e32 v13, v195, v196
	v_mov_b32_e32 v12, v197
	v_mul_f32_e32 v15, v198, v199
	v_mov_b32_e32 v14, v200
	v_mul_f32_e32 v17, v201, v202
	v_mov_b32_e32 v10, v203
	v_mul_f32_e32 v9, v204, v205
	ds_write_b32 v16, v13 offset:2048
	ds_write_b32 v16, v15 offset:3072
	ds_write_b32 v16, v17 offset:4096
	ds_write_b32 v16, v9 offset:5120
	v_mov_b32_e32 v164, v8
	v_lshlrev_b32_e32 v0, 2, v8
	v_mov_b32_e32 v6, 0
	v_add_u32_e32 v16, 0, v0
	s_add_i32 s0, 0, 0x800
	v_sub_u32_e32 v18, 0, v0
	s_mov_b32 s1, 0
	v_mov_b32_e32 v7, v6
	v_mov_b32_e32 v4, v6
	v_mov_b32_e32 v5, v6
	s_waitcnt lgkmcnt(0)
	s_barrier
